# final pass variant: 8-byte h2b loads so every store instruction writes a contiguous 1 KiB (lane*16) instead of 16 B out of every 32 B
# speedup vs baseline: 1.0153x; 1.0029x over previous
; __device__ __forceinline__ void final_pass(const Params& p, int G) {
;     ...
;     const int lane = threadIdx.x & 63, gw = blockIdx.x * NWAVES + (threadIdx.x >> 6), NGW = G * NWAVES;
;     for (int m = gw; m < T; m += NGW) {
;         const float rstd = __builtin_amdgcn_rsqf(ctl[CF_SS3 + m] * (1.f / DM) + EPS);
;         const u32x4* hr = (const u32x4*)(h2b + (size_t)m * DM) + lane; f32x4* xr = (f32x4*)(p.out + (size_t)m * DM) + 2 * lane; const f32x4* gr = (const f32x4*)p.fin_g + 2 * lane;
;         u32x4 hv[8];
; #pragma unroll
;         for (int j = 0; j < 8; ++j) hv[j] = hr[64 * j];
.LBB0_1051:
	s_cmp_lt_i32 s40, 9
	s_cselect_b64 s[0:1], -1, 0
	s_and_b64 s[0:1], s[0:1], s[2:3]
	s_andn2_b64 vcc, exec, s[0:1]
	s_cbranch_vccnz .LBB0_1055
	v_lshrrev_b32_e32 v0, 6, v208
	v_lshl_add_u32 v12, s46, 3, v0
	s_movk_i32 s0, 0x4000
	v_cmp_gt_i32_e32 vcc, s0, v12
	s_and_saveexec_b64 s[0:1], vcc
	s_cbranch_execz .LBB0_1055
	v_and_b32_e32 v4, 63, v208
	v_lshlrev_b32_e32 v0, 5, v4
	v_mov_b32_e32 v1, 0
	v_lshl_add_u64 v[14:15], s[82:83], 0, v[0:1]
	s_mov_b64 s[2:3], 0x1000
	v_lshl_add_u64 v[16:17], v[14:15], 0, s[2:3]
	s_mov_b64 s[2:3], 0x1800
	v_lshl_add_u64 v[18:19], v[14:15], 0, s[2:3]
	s_mov_b64 s[2:3], 0x2000
	v_lshl_add_u64 v[20:21], v[14:15], 0, s[2:3]
	s_mov_b64 s[2:3], 0x2800
	v_ashrrev_i32_e32 v13, 31, v12
	s_waitcnt lgkmcnt(0)
	v_mov_b64_e32 v[2:3], 0x40000
	s_lshl_b32 s0, s90, 3
	v_lshl_add_u64 v[22:23], v[14:15], 0, s[2:3]
	s_mov_b64 s[2:3], 0x3000
	v_lshl_add_u64 v[28:29], v[12:13], 2, v[2:3]
	v_lshlrev_b64 v[2:3], 14, v[12:13]
	v_lshl_add_u64 v[24:25], v[14:15], 0, s[2:3]
	s_mov_b64 s[2:3], 0x3800
	s_ashr_i32 s1, s0, 31
	v_lshlrev_b64 v[30:31], 13, v[12:13]
	v_or_b32_e32 v2, v2, v0
	v_lshl_add_u64 v[26:27], v[14:15], 0, s[2:3]
	s_lshl_b64 s[2:3], s[0:1], 2
	v_lshl_or_b32 v30, v4, 4, v30
	s_lshl_b64 s[4:5], s[0:1], 13
	v_lshl_add_u64 v[32:33], s[84:85], 0, v[2:3]
	s_lshl_b64 s[6:7], s[0:1], 14
	s_mov_b64 s[8:9], 0
	v_mov_b32_e32 v13, 0x358637bd
	s_mov_b32 s1, 0x35fa1000
	s_movk_i32 s10, 0x1000
	s_movk_i32 s11, 0x2000
	s_movk_i32 s12, 0x3000
	s_movk_i32 s13, 0x3fff
	v_lshlrev_b32_e32 v5, 3, v4
	v_lshlrev_b32_e32 v6, 4, v4
	v_sub_u32_e32 v30, v30, v5
	v_sub_co_u32_e32 v32, vcc, v32, v6
	s_nop 1
	v_subbrev_co_u32_e32 v33, vcc, 0, v33, vcc
	v_sub_co_u32_e32 v14, vcc, v14, v6
	s_nop 1
	v_subbrev_co_u32_e32 v15, vcc, 0, v15, vcc
	s_mov_b64 s[16:17], 0x1000
	s_mov_b64 s[18:19], 0x2000
	s_mov_b64 s[20:21], 0x3000
	v_lshl_add_u64 v[16:17], v[14:15], 0, s[16:17]
	v_lshl_add_u64 v[18:19], v[14:15], 0, s[18:19]
	v_lshl_add_u64 v[20:21], v[14:15], 0, s[20:21]
	global_load_dwordx4 v[68:71], v[14:15], off
	global_load_dwordx4 v[72:75], v[14:15], off offset:1024
	global_load_dwordx4 v[76:79], v[14:15], off offset:2048
	global_load_dwordx4 v[80:83], v[14:15], off offset:3072
	global_load_dwordx4 v[84:87], v[16:17], off
	global_load_dwordx4 v[88:91], v[16:17], off offset:1024
	global_load_dwordx4 v[92:95], v[16:17], off offset:2048
	global_load_dwordx4 v[96:99], v[16:17], off offset:3072
	global_load_dwordx4 v[100:103], v[18:19], off
	global_load_dwordx4 v[104:107], v[18:19], off offset:1024
	global_load_dwordx4 v[108:111], v[18:19], off offset:2048
	global_load_dwordx4 v[112:115], v[18:19], off offset:3072
	global_load_dwordx4 v[116:119], v[20:21], off
	global_load_dwordx4 v[120:123], v[20:21], off offset:1024
	global_load_dwordx4 v[124:127], v[20:21], off offset:2048
	global_load_dwordx4 v[128:131], v[20:21], off offset:3072
	v_readfirstlane_b32 s14, v12
	v_lshl_add_u64 v[0:1], s[86:87], 0, v[28:29]
	global_load_dword v196, v[0:1], off
	v_lshl_add_u64 v[2:3], s[86:87], 0, v[30:31]
	v_add_co_u32_e32 v34, vcc, 0x35fa0000, v2
	s_nop 1
	v_addc_co_u32_e32 v35, vcc, 0, v3, vcc
	v_add_co_u32_e32 v64, vcc, s1, v2
	s_nop 1
	v_addc_co_u32_e32 v65, vcc, 0, v3, vcc
	global_load_dwordx2 v[132:133], v[34:35], off
	global_load_dwordx2 v[134:135], v[34:35], off offset:512
	global_load_dwordx2 v[136:137], v[34:35], off offset:1024
	global_load_dwordx2 v[138:139], v[34:35], off offset:1536
	global_load_dwordx2 v[140:141], v[34:35], off offset:2048
	global_load_dwordx2 v[142:143], v[34:35], off offset:2560
	global_load_dwordx2 v[144:145], v[34:35], off offset:3072
	global_load_dwordx2 v[146:147], v[34:35], off offset:3584
	global_load_dwordx2 v[148:149], v[64:65], off
	global_load_dwordx2 v[150:151], v[64:65], off offset:512
	global_load_dwordx2 v[152:153], v[64:65], off offset:1024
	global_load_dwordx2 v[154:155], v[64:65], off offset:1536
	global_load_dwordx2 v[156:157], v[64:65], off offset:2048
	global_load_dwordx2 v[158:159], v[64:65], off offset:2560
	global_load_dwordx2 v[160:161], v[64:65], off offset:3072
	global_load_dwordx2 v[162:163], v[64:65], off offset:3584
	v_lshl_add_u64 v[28:29], v[28:29], 0, s[2:3]
	v_lshl_add_u64 v[30:31], v[30:31], 0, s[4:5]
.Lfin_loop:
	s_add_i32 s15, s14, s0
	s_cmp_lt_i32 s15, 0x4000
	s_cbranch_scc0 .Lfin_last_a
; __device__ __forceinline__ void final_pass(const Params& p, int G) {
;     ...
;         for (int j = 0; j < 8; ++j) hv[j] = hr[64 * j];
; #pragma unroll
;         for (int j = 0; j < 8; ++j) { const u32x4 w = hv[j]; const f32x4 g0 = gr[128 * j], g1 = gr[128 * j + 1];
;             const f32x4 v0 = (f32x4){__builtin_bit_cast(float, w.x << 16), __builtin_bit_cast(float, w.x & 0xffff0000u), __builtin_bit_cast(float, w.y << 16), __builtin_bit_cast(float, w.y & 0xffff0000u)};
;             const f32x4 v1 = (f32x4){__builtin_bit_cast(float, w.z << 16), __builtin_bit_cast(float, w.z & 0xffff0000u), __builtin_bit_cast(float, w.w << 16), __builtin_bit_cast(float, w.w & 0xffff0000u)};
;             __builtin_nontemporal_store(v0 * rstd * g0, xr + 128 * j); __builtin_nontemporal_store(v1 * rstd * g1, xr + 128 * j + 1); }
	v_lshl_add_u64 v[0:1], s[86:87], 0, v[28:29]
	global_load_dword v197, v[0:1], off
	v_lshl_add_u64 v[2:3], s[86:87], 0, v[30:31]
	v_add_co_u32_e32 v34, vcc, 0x35fa0000, v2
	s_nop 1
	v_addc_co_u32_e32 v35, vcc, 0, v3, vcc
	v_add_co_u32_e32 v64, vcc, s1, v2
	s_nop 1
	v_addc_co_u32_e32 v65, vcc, 0, v3, vcc
	global_load_dwordx2 v[164:165], v[34:35], off
	global_load_dwordx2 v[166:167], v[34:35], off offset:512
	global_load_dwordx2 v[168:169], v[34:35], off offset:1024
	global_load_dwordx2 v[170:171], v[34:35], off offset:1536
	global_load_dwordx2 v[172:173], v[34:35], off offset:2048
	global_load_dwordx2 v[174:175], v[34:35], off offset:2560
	global_load_dwordx2 v[176:177], v[34:35], off offset:3072
	global_load_dwordx2 v[178:179], v[34:35], off offset:3584
	global_load_dwordx2 v[180:181], v[64:65], off
	global_load_dwordx2 v[182:183], v[64:65], off offset:512
	global_load_dwordx2 v[184:185], v[64:65], off offset:1024
	global_load_dwordx2 v[186:187], v[64:65], off offset:1536
	global_load_dwordx2 v[188:189], v[64:65], off offset:2048
	global_load_dwordx2 v[190:191], v[64:65], off offset:2560
	global_load_dwordx2 v[192:193], v[64:65], off offset:3072
	global_load_dwordx2 v[194:195], v[64:65], off offset:3584
	v_lshl_add_u64 v[28:29], v[28:29], 0, s[2:3]
	v_lshl_add_u64 v[30:31], v[30:31], 0, s[4:5]
	s_waitcnt vmcnt(17)
	v_fmamk_f32 v36, v196, 0x39800000, v13
	v_rsq_f32_e32 v36, v36
	v_lshl_add_u64 v[38:39], v[32:33], 0, s[16:17]
	v_lshl_add_u64 v[40:41], v[32:33], 0, s[18:19]
	v_lshl_add_u64 v[42:43], v[32:33], 0, s[20:21]
	v_lshlrev_b32_e32 v216, 16, v132
	v_and_b32_e32 v217, 0xffff0000, v132
	v_lshlrev_b32_e32 v218, 16, v133
	v_and_b32_e32 v219, 0xffff0000, v133
	v_lshlrev_b32_e32 v220, 16, v134
	v_and_b32_e32 v221, 0xffff0000, v134
	v_lshlrev_b32_e32 v222, 16, v135
	v_and_b32_e32 v223, 0xffff0000, v135
	v_pk_mul_f32 v[216:217], v[36:37], v[216:217] op_sel_hi:[0,1]
	v_pk_mul_f32 v[218:219], v[36:37], v[218:219] op_sel_hi:[0,1]
	v_pk_mul_f32 v[220:221], v[36:37], v[220:221] op_sel_hi:[0,1]
	v_pk_mul_f32 v[222:223], v[36:37], v[222:223] op_sel_hi:[0,1]
	v_pk_mul_f32 v[216:217], v[216:217], v[68:69]
	v_pk_mul_f32 v[218:219], v[218:219], v[70:71]
	v_pk_mul_f32 v[220:221], v[220:221], v[72:73]
	v_pk_mul_f32 v[222:223], v[222:223], v[74:75]
	global_store_dwordx4 v[32:33], v[216:219], off nt
	global_store_dwordx4 v[32:33], v[220:223], off offset:1024 nt
	s_nop 1
	v_lshlrev_b32_e32 v216, 16, v136
	v_and_b32_e32 v217, 0xffff0000, v136
	v_lshlrev_b32_e32 v218, 16, v137
	v_and_b32_e32 v219, 0xffff0000, v137
	v_lshlrev_b32_e32 v220, 16, v138
	v_and_b32_e32 v221, 0xffff0000, v138
	v_lshlrev_b32_e32 v222, 16, v139
	v_and_b32_e32 v223, 0xffff0000, v139
	v_pk_mul_f32 v[216:217], v[36:37], v[216:217] op_sel_hi:[0,1]
	v_pk_mul_f32 v[218:219], v[36:37], v[218:219] op_sel_hi:[0,1]
	v_pk_mul_f32 v[220:221], v[36:37], v[220:221] op_sel_hi:[0,1]
	v_pk_mul_f32 v[222:223], v[36:37], v[222:223] op_sel_hi:[0,1]
	v_pk_mul_f32 v[216:217], v[216:217], v[76:77]
	v_pk_mul_f32 v[218:219], v[218:219], v[78:79]
	v_pk_mul_f32 v[220:221], v[220:221], v[80:81]
	v_pk_mul_f32 v[222:223], v[222:223], v[82:83]
	global_store_dwordx4 v[32:33], v[216:219], off offset:2048 nt
	global_store_dwordx4 v[32:33], v[220:223], off offset:3072 nt
	s_nop 1
	v_lshlrev_b32_e32 v216, 16, v140
	v_and_b32_e32 v217, 0xffff0000, v140
	v_lshlrev_b32_e32 v218, 16, v141
	v_and_b32_e32 v219, 0xffff0000, v141
	v_lshlrev_b32_e32 v220, 16, v142
	v_and_b32_e32 v221, 0xffff0000, v142
	v_lshlrev_b32_e32 v222, 16, v143
	v_and_b32_e32 v223, 0xffff0000, v143
	v_pk_mul_f32 v[216:217], v[36:37], v[216:217] op_sel_hi:[0,1]
	v_pk_mul_f32 v[218:219], v[36:37], v[218:219] op_sel_hi:[0,1]
	v_pk_mul_f32 v[220:221], v[36:37], v[220:221] op_sel_hi:[0,1]
	v_pk_mul_f32 v[222:223], v[36:37], v[222:223] op_sel_hi:[0,1]
	v_pk_mul_f32 v[216:217], v[216:217], v[84:85]
	v_pk_mul_f32 v[218:219], v[218:219], v[86:87]
	v_pk_mul_f32 v[220:221], v[220:221], v[88:89]
	v_pk_mul_f32 v[222:223], v[222:223], v[90:91]
	global_store_dwordx4 v[38:39], v[216:219], off nt
	global_store_dwordx4 v[38:39], v[220:223], off offset:1024 nt
	s_nop 1
	v_lshlrev_b32_e32 v216, 16, v144
	v_and_b32_e32 v217, 0xffff0000, v144
	v_lshlrev_b32_e32 v218, 16, v145
	v_and_b32_e32 v219, 0xffff0000, v145
	v_lshlrev_b32_e32 v220, 16, v146
	v_and_b32_e32 v221, 0xffff0000, v146
	v_lshlrev_b32_e32 v222, 16, v147
	v_and_b32_e32 v223, 0xffff0000, v147
	v_pk_mul_f32 v[216:217], v[36:37], v[216:217] op_sel_hi:[0,1]
	v_pk_mul_f32 v[218:219], v[36:37], v[218:219] op_sel_hi:[0,1]
	v_pk_mul_f32 v[220:221], v[36:37], v[220:221] op_sel_hi:[0,1]
	v_pk_mul_f32 v[222:223], v[36:37], v[222:223] op_sel_hi:[0,1]
	v_pk_mul_f32 v[216:217], v[216:217], v[92:93]
	v_pk_mul_f32 v[218:219], v[218:219], v[94:95]
	v_pk_mul_f32 v[220:221], v[220:221], v[96:97]
	v_pk_mul_f32 v[222:223], v[222:223], v[98:99]
	global_store_dwordx4 v[38:39], v[216:219], off offset:2048 nt
	global_store_dwordx4 v[38:39], v[220:223], off offset:3072 nt
	s_nop 1
	v_lshlrev_b32_e32 v216, 16, v148
	v_and_b32_e32 v217, 0xffff0000, v148
	v_lshlrev_b32_e32 v218, 16, v149
	v_and_b32_e32 v219, 0xffff0000, v149
	v_lshlrev_b32_e32 v220, 16, v150
	v_and_b32_e32 v221, 0xffff0000, v150
	v_lshlrev_b32_e32 v222, 16, v151
	v_and_b32_e32 v223, 0xffff0000, v151
	v_pk_mul_f32 v[216:217], v[36:37], v[216:217] op_sel_hi:[0,1]
	v_pk_mul_f32 v[218:219], v[36:37], v[218:219] op_sel_hi:[0,1]
	v_pk_mul_f32 v[220:221], v[36:37], v[220:221] op_sel_hi:[0,1]
	v_pk_mul_f32 v[222:223], v[36:37], v[222:223] op_sel_hi:[0,1]
	v_pk_mul_f32 v[216:217], v[216:217], v[100:101]
	v_pk_mul_f32 v[218:219], v[218:219], v[102:103]
	v_pk_mul_f32 v[220:221], v[220:221], v[104:105]
; __device__ __forceinline__ void final_pass(const Params& p, int G) {
;     ...
;         for (int j = 0; j < 8; ++j) hv[j] = hr[64 * j];
; #pragma unroll
;         for (int j = 0; j < 8; ++j) { const u32x4 w = hv[j]; const f32x4 g0 = gr[128 * j], g1 = gr[128 * j + 1];
;             const f32x4 v0 = (f32x4){__builtin_bit_cast(float, w.x << 16), __builtin_bit_cast(float, w.x & 0xffff0000u), __builtin_bit_cast(float, w.y << 16), __builtin_bit_cast(float, w.y & 0xffff0000u)};
;             const f32x4 v1 = (f32x4){__builtin_bit_cast(float, w.z << 16), __builtin_bit_cast(float, w.z & 0xffff0000u), __builtin_bit_cast(float, w.w << 16), __builtin_bit_cast(float, w.w & 0xffff0000u)};
;             __builtin_nontemporal_store(v0 * rstd * g0, xr + 128 * j); __builtin_nontemporal_store(v1 * rstd * g1, xr + 128 * j + 1); }
	v_pk_mul_f32 v[222:223], v[222:223], v[106:107]
	global_store_dwordx4 v[40:41], v[216:219], off nt
	global_store_dwordx4 v[40:41], v[220:223], off offset:1024 nt
	s_nop 1
	v_lshlrev_b32_e32 v216, 16, v152
	v_and_b32_e32 v217, 0xffff0000, v152
	v_lshlrev_b32_e32 v218, 16, v153
	v_and_b32_e32 v219, 0xffff0000, v153
	v_lshlrev_b32_e32 v220, 16, v154
	v_and_b32_e32 v221, 0xffff0000, v154
	v_lshlrev_b32_e32 v222, 16, v155
	v_and_b32_e32 v223, 0xffff0000, v155
	v_pk_mul_f32 v[216:217], v[36:37], v[216:217] op_sel_hi:[0,1]
	v_pk_mul_f32 v[218:219], v[36:37], v[218:219] op_sel_hi:[0,1]
	v_pk_mul_f32 v[220:221], v[36:37], v[220:221] op_sel_hi:[0,1]
	v_pk_mul_f32 v[222:223], v[36:37], v[222:223] op_sel_hi:[0,1]
	v_pk_mul_f32 v[216:217], v[216:217], v[108:109]
	v_pk_mul_f32 v[218:219], v[218:219], v[110:111]
	v_pk_mul_f32 v[220:221], v[220:221], v[112:113]
	v_pk_mul_f32 v[222:223], v[222:223], v[114:115]
	global_store_dwordx4 v[40:41], v[216:219], off offset:2048 nt
	global_store_dwordx4 v[40:41], v[220:223], off offset:3072 nt
	s_nop 1
	v_lshlrev_b32_e32 v216, 16, v156
	v_and_b32_e32 v217, 0xffff0000, v156
	v_lshlrev_b32_e32 v218, 16, v157
	v_and_b32_e32 v219, 0xffff0000, v157
	v_lshlrev_b32_e32 v220, 16, v158
	v_and_b32_e32 v221, 0xffff0000, v158
	v_lshlrev_b32_e32 v222, 16, v159
	v_and_b32_e32 v223, 0xffff0000, v159
	v_pk_mul_f32 v[216:217], v[36:37], v[216:217] op_sel_hi:[0,1]
	v_pk_mul_f32 v[218:219], v[36:37], v[218:219] op_sel_hi:[0,1]
	v_pk_mul_f32 v[220:221], v[36:37], v[220:221] op_sel_hi:[0,1]
	v_pk_mul_f32 v[222:223], v[36:37], v[222:223] op_sel_hi:[0,1]
	v_pk_mul_f32 v[216:217], v[216:217], v[116:117]
	v_pk_mul_f32 v[218:219], v[218:219], v[118:119]
	v_pk_mul_f32 v[220:221], v[220:221], v[120:121]
	v_pk_mul_f32 v[222:223], v[222:223], v[122:123]
	global_store_dwordx4 v[42:43], v[216:219], off nt
	global_store_dwordx4 v[42:43], v[220:223], off offset:1024 nt
	s_nop 1
	v_lshlrev_b32_e32 v216, 16, v160
	v_and_b32_e32 v217, 0xffff0000, v160
	v_lshlrev_b32_e32 v218, 16, v161
	v_and_b32_e32 v219, 0xffff0000, v161
	v_lshlrev_b32_e32 v220, 16, v162
	v_and_b32_e32 v221, 0xffff0000, v162
	v_lshlrev_b32_e32 v222, 16, v163
	v_and_b32_e32 v223, 0xffff0000, v163
	v_pk_mul_f32 v[216:217], v[36:37], v[216:217] op_sel_hi:[0,1]
	v_pk_mul_f32 v[218:219], v[36:37], v[218:219] op_sel_hi:[0,1]
	v_pk_mul_f32 v[220:221], v[36:37], v[220:221] op_sel_hi:[0,1]
	v_pk_mul_f32 v[222:223], v[36:37], v[222:223] op_sel_hi:[0,1]
	v_pk_mul_f32 v[216:217], v[216:217], v[124:125]
	v_pk_mul_f32 v[218:219], v[218:219], v[126:127]
	v_pk_mul_f32 v[220:221], v[220:221], v[128:129]
	v_pk_mul_f32 v[222:223], v[222:223], v[130:131]
	global_store_dwordx4 v[42:43], v[216:219], off offset:2048 nt
	global_store_dwordx4 v[42:43], v[220:223], off offset:3072 nt
	s_nop 1
	v_lshl_add_u64 v[32:33], v[32:33], 0, s[6:7]
	s_mov_b32 s14, s15
	s_add_i32 s15, s14, s0
	s_cmp_lt_i32 s15, 0x4000
	s_cbranch_scc0 .Lfin_last_b
	v_lshl_add_u64 v[0:1], s[86:87], 0, v[28:29]
	global_load_dword v196, v[0:1], off
	v_lshl_add_u64 v[2:3], s[86:87], 0, v[30:31]
	v_add_co_u32_e32 v34, vcc, 0x35fa0000, v2
	s_nop 1
	v_addc_co_u32_e32 v35, vcc, 0, v3, vcc
	v_add_co_u32_e32 v64, vcc, s1, v2
	s_nop 1
	v_addc_co_u32_e32 v65, vcc, 0, v3, vcc
	global_load_dwordx2 v[132:133], v[34:35], off
	global_load_dwordx2 v[134:135], v[34:35], off offset:512
	global_load_dwordx2 v[136:137], v[34:35], off offset:1024
	global_load_dwordx2 v[138:139], v[34:35], off offset:1536
	global_load_dwordx2 v[140:141], v[34:35], off offset:2048
	global_load_dwordx2 v[142:143], v[34:35], off offset:2560
	global_load_dwordx2 v[144:145], v[34:35], off offset:3072
	global_load_dwordx2 v[146:147], v[34:35], off offset:3584
	global_load_dwordx2 v[148:149], v[64:65], off
	global_load_dwordx2 v[150:151], v[64:65], off offset:512
	global_load_dwordx2 v[152:153], v[64:65], off offset:1024
	global_load_dwordx2 v[154:155], v[64:65], off offset:1536
	global_load_dwordx2 v[156:157], v[64:65], off offset:2048
	global_load_dwordx2 v[158:159], v[64:65], off offset:2560
	global_load_dwordx2 v[160:161], v[64:65], off offset:3072
	global_load_dwordx2 v[162:163], v[64:65], off offset:3584
	v_lshl_add_u64 v[28:29], v[28:29], 0, s[2:3]
	v_lshl_add_u64 v[30:31], v[30:31], 0, s[4:5]
	s_waitcnt vmcnt(17)
; __device__ __forceinline__ void final_pass(const Params& p, int G) {
;     ...
;         for (int j = 0; j < 8; ++j) hv[j] = hr[64 * j];
; #pragma unroll
;         for (int j = 0; j < 8; ++j) { const u32x4 w = hv[j]; const f32x4 g0 = gr[128 * j], g1 = gr[128 * j + 1];
;             const f32x4 v0 = (f32x4){__builtin_bit_cast(float, w.x << 16), __builtin_bit_cast(float, w.x & 0xffff0000u), __builtin_bit_cast(float, w.y << 16), __builtin_bit_cast(float, w.y & 0xffff0000u)};
;             const f32x4 v1 = (f32x4){__builtin_bit_cast(float, w.z << 16), __builtin_bit_cast(float, w.z & 0xffff0000u), __builtin_bit_cast(float, w.w << 16), __builtin_bit_cast(float, w.w & 0xffff0000u)};
;             __builtin_nontemporal_store(v0 * rstd * g0, xr + 128 * j); __builtin_nontemporal_store(v1 * rstd * g1, xr + 128 * j + 1); }
	v_fmamk_f32 v36, v197, 0x39800000, v13
	v_rsq_f32_e32 v36, v36
	v_lshl_add_u64 v[38:39], v[32:33], 0, s[16:17]
	v_lshl_add_u64 v[40:41], v[32:33], 0, s[18:19]
	v_lshl_add_u64 v[42:43], v[32:33], 0, s[20:21]
	v_lshlrev_b32_e32 v216, 16, v164
	v_and_b32_e32 v217, 0xffff0000, v164
	v_lshlrev_b32_e32 v218, 16, v165
	v_and_b32_e32 v219, 0xffff0000, v165
	v_lshlrev_b32_e32 v220, 16, v166
	v_and_b32_e32 v221, 0xffff0000, v166
	v_lshlrev_b32_e32 v222, 16, v167
	v_and_b32_e32 v223, 0xffff0000, v167
	v_pk_mul_f32 v[216:217], v[36:37], v[216:217] op_sel_hi:[0,1]
	v_pk_mul_f32 v[218:219], v[36:37], v[218:219] op_sel_hi:[0,1]
	v_pk_mul_f32 v[220:221], v[36:37], v[220:221] op_sel_hi:[0,1]
	v_pk_mul_f32 v[222:223], v[36:37], v[222:223] op_sel_hi:[0,1]
	v_pk_mul_f32 v[216:217], v[216:217], v[68:69]
	v_pk_mul_f32 v[218:219], v[218:219], v[70:71]
	v_pk_mul_f32 v[220:221], v[220:221], v[72:73]
	v_pk_mul_f32 v[222:223], v[222:223], v[74:75]
	global_store_dwordx4 v[32:33], v[216:219], off nt
	global_store_dwordx4 v[32:33], v[220:223], off offset:1024 nt
	s_nop 1
	v_lshlrev_b32_e32 v216, 16, v168
	v_and_b32_e32 v217, 0xffff0000, v168
	v_lshlrev_b32_e32 v218, 16, v169
	v_and_b32_e32 v219, 0xffff0000, v169
	v_lshlrev_b32_e32 v220, 16, v170
	v_and_b32_e32 v221, 0xffff0000, v170
	v_lshlrev_b32_e32 v222, 16, v171
	v_and_b32_e32 v223, 0xffff0000, v171
	v_pk_mul_f32 v[216:217], v[36:37], v[216:217] op_sel_hi:[0,1]
	v_pk_mul_f32 v[218:219], v[36:37], v[218:219] op_sel_hi:[0,1]
	v_pk_mul_f32 v[220:221], v[36:37], v[220:221] op_sel_hi:[0,1]
	v_pk_mul_f32 v[222:223], v[36:37], v[222:223] op_sel_hi:[0,1]
	v_pk_mul_f32 v[216:217], v[216:217], v[76:77]
	v_pk_mul_f32 v[218:219], v[218:219], v[78:79]
	v_pk_mul_f32 v[220:221], v[220:221], v[80:81]
	v_pk_mul_f32 v[222:223], v[222:223], v[82:83]
	global_store_dwordx4 v[32:33], v[216:219], off offset:2048 nt
	global_store_dwordx4 v[32:33], v[220:223], off offset:3072 nt
	s_nop 1
	v_lshlrev_b32_e32 v216, 16, v172
	v_and_b32_e32 v217, 0xffff0000, v172
	v_lshlrev_b32_e32 v218, 16, v173
	v_and_b32_e32 v219, 0xffff0000, v173
	v_lshlrev_b32_e32 v220, 16, v174
	v_and_b32_e32 v221, 0xffff0000, v174
	v_lshlrev_b32_e32 v222, 16, v175
	v_and_b32_e32 v223, 0xffff0000, v175
	v_pk_mul_f32 v[216:217], v[36:37], v[216:217] op_sel_hi:[0,1]
	v_pk_mul_f32 v[218:219], v[36:37], v[218:219] op_sel_hi:[0,1]
	v_pk_mul_f32 v[220:221], v[36:37], v[220:221] op_sel_hi:[0,1]
	v_pk_mul_f32 v[222:223], v[36:37], v[222:223] op_sel_hi:[0,1]
	v_pk_mul_f32 v[216:217], v[216:217], v[84:85]
	v_pk_mul_f32 v[218:219], v[218:219], v[86:87]
	v_pk_mul_f32 v[220:221], v[220:221], v[88:89]
	v_pk_mul_f32 v[222:223], v[222:223], v[90:91]
	global_store_dwordx4 v[38:39], v[216:219], off nt
	global_store_dwordx4 v[38:39], v[220:223], off offset:1024 nt
	s_nop 1
	v_lshlrev_b32_e32 v216, 16, v176
	v_and_b32_e32 v217, 0xffff0000, v176
	v_lshlrev_b32_e32 v218, 16, v177
	v_and_b32_e32 v219, 0xffff0000, v177
	v_lshlrev_b32_e32 v220, 16, v178
	v_and_b32_e32 v221, 0xffff0000, v178
	v_lshlrev_b32_e32 v222, 16, v179
	v_and_b32_e32 v223, 0xffff0000, v179
	v_pk_mul_f32 v[216:217], v[36:37], v[216:217] op_sel_hi:[0,1]
	v_pk_mul_f32 v[218:219], v[36:37], v[218:219] op_sel_hi:[0,1]
	v_pk_mul_f32 v[220:221], v[36:37], v[220:221] op_sel_hi:[0,1]
	v_pk_mul_f32 v[222:223], v[36:37], v[222:223] op_sel_hi:[0,1]
	v_pk_mul_f32 v[216:217], v[216:217], v[92:93]
	v_pk_mul_f32 v[218:219], v[218:219], v[94:95]
	v_pk_mul_f32 v[220:221], v[220:221], v[96:97]
	v_pk_mul_f32 v[222:223], v[222:223], v[98:99]
	global_store_dwordx4 v[38:39], v[216:219], off offset:2048 nt
	global_store_dwordx4 v[38:39], v[220:223], off offset:3072 nt
	s_nop 1
	v_lshlrev_b32_e32 v216, 16, v180
	v_and_b32_e32 v217, 0xffff0000, v180
	v_lshlrev_b32_e32 v218, 16, v181
	v_and_b32_e32 v219, 0xffff0000, v181
	v_lshlrev_b32_e32 v220, 16, v182
	v_and_b32_e32 v221, 0xffff0000, v182
	v_lshlrev_b32_e32 v222, 16, v183
	v_and_b32_e32 v223, 0xffff0000, v183
	v_pk_mul_f32 v[216:217], v[36:37], v[216:217] op_sel_hi:[0,1]
	v_pk_mul_f32 v[218:219], v[36:37], v[218:219] op_sel_hi:[0,1]
	v_pk_mul_f32 v[220:221], v[36:37], v[220:221] op_sel_hi:[0,1]
	v_pk_mul_f32 v[222:223], v[36:37], v[222:223] op_sel_hi:[0,1]
	v_pk_mul_f32 v[216:217], v[216:217], v[100:101]
	v_pk_mul_f32 v[218:219], v[218:219], v[102:103]
	v_pk_mul_f32 v[220:221], v[220:221], v[104:105]
	v_pk_mul_f32 v[222:223], v[222:223], v[106:107]
	global_store_dwordx4 v[40:41], v[216:219], off nt
	global_store_dwordx4 v[40:41], v[220:223], off offset:1024 nt
	s_nop 1
	v_lshlrev_b32_e32 v216, 16, v184
	v_and_b32_e32 v217, 0xffff0000, v184
	v_lshlrev_b32_e32 v218, 16, v185
	v_and_b32_e32 v219, 0xffff0000, v185
	v_lshlrev_b32_e32 v220, 16, v186
	v_and_b32_e32 v221, 0xffff0000, v186
	v_lshlrev_b32_e32 v222, 16, v187
	v_and_b32_e32 v223, 0xffff0000, v187
	v_pk_mul_f32 v[216:217], v[36:37], v[216:217] op_sel_hi:[0,1]
	v_pk_mul_f32 v[218:219], v[36:37], v[218:219] op_sel_hi:[0,1]
	v_pk_mul_f32 v[220:221], v[36:37], v[220:221] op_sel_hi:[0,1]
	v_pk_mul_f32 v[222:223], v[36:37], v[222:223] op_sel_hi:[0,1]
	v_pk_mul_f32 v[216:217], v[216:217], v[108:109]
	v_pk_mul_f32 v[218:219], v[218:219], v[110:111]
	v_pk_mul_f32 v[220:221], v[220:221], v[112:113]
	v_pk_mul_f32 v[222:223], v[222:223], v[114:115]
	global_store_dwordx4 v[40:41], v[216:219], off offset:2048 nt
	global_store_dwordx4 v[40:41], v[220:223], off offset:3072 nt
	s_nop 1
	v_lshlrev_b32_e32 v216, 16, v188
	v_and_b32_e32 v217, 0xffff0000, v188
	v_lshlrev_b32_e32 v218, 16, v189
	v_and_b32_e32 v219, 0xffff0000, v189
	v_lshlrev_b32_e32 v220, 16, v190
	v_and_b32_e32 v221, 0xffff0000, v190
	v_lshlrev_b32_e32 v222, 16, v191
	v_and_b32_e32 v223, 0xffff0000, v191
; __device__ __forceinline__ void final_pass(const Params& p, int G) {
;     ...
;         for (int j = 0; j < 8; ++j) hv[j] = hr[64 * j];
; #pragma unroll
;         for (int j = 0; j < 8; ++j) { const u32x4 w = hv[j]; const f32x4 g0 = gr[128 * j], g1 = gr[128 * j + 1];
;             const f32x4 v0 = (f32x4){__builtin_bit_cast(float, w.x << 16), __builtin_bit_cast(float, w.x & 0xffff0000u), __builtin_bit_cast(float, w.y << 16), __builtin_bit_cast(float, w.y & 0xffff0000u)};
;             const f32x4 v1 = (f32x4){__builtin_bit_cast(float, w.z << 16), __builtin_bit_cast(float, w.z & 0xffff0000u), __builtin_bit_cast(float, w.w << 16), __builtin_bit_cast(float, w.w & 0xffff0000u)};
;             __builtin_nontemporal_store(v0 * rstd * g0, xr + 128 * j); __builtin_nontemporal_store(v1 * rstd * g1, xr + 128 * j + 1); }
	v_pk_mul_f32 v[216:217], v[36:37], v[216:217] op_sel_hi:[0,1]
	v_pk_mul_f32 v[218:219], v[36:37], v[218:219] op_sel_hi:[0,1]
	v_pk_mul_f32 v[220:221], v[36:37], v[220:221] op_sel_hi:[0,1]
	v_pk_mul_f32 v[222:223], v[36:37], v[222:223] op_sel_hi:[0,1]
	v_pk_mul_f32 v[216:217], v[216:217], v[116:117]
	v_pk_mul_f32 v[218:219], v[218:219], v[118:119]
	v_pk_mul_f32 v[220:221], v[220:221], v[120:121]
	v_pk_mul_f32 v[222:223], v[222:223], v[122:123]
	global_store_dwordx4 v[42:43], v[216:219], off nt
	global_store_dwordx4 v[42:43], v[220:223], off offset:1024 nt
	s_nop 1
	v_lshlrev_b32_e32 v216, 16, v192
	v_and_b32_e32 v217, 0xffff0000, v192
	v_lshlrev_b32_e32 v218, 16, v193
	v_and_b32_e32 v219, 0xffff0000, v193
	v_lshlrev_b32_e32 v220, 16, v194
	v_and_b32_e32 v221, 0xffff0000, v194
	v_lshlrev_b32_e32 v222, 16, v195
	v_and_b32_e32 v223, 0xffff0000, v195
	v_pk_mul_f32 v[216:217], v[36:37], v[216:217] op_sel_hi:[0,1]
	v_pk_mul_f32 v[218:219], v[36:37], v[218:219] op_sel_hi:[0,1]
	v_pk_mul_f32 v[220:221], v[36:37], v[220:221] op_sel_hi:[0,1]
	v_pk_mul_f32 v[222:223], v[36:37], v[222:223] op_sel_hi:[0,1]
	v_pk_mul_f32 v[216:217], v[216:217], v[124:125]
	v_pk_mul_f32 v[218:219], v[218:219], v[126:127]
	v_pk_mul_f32 v[220:221], v[220:221], v[128:129]
	v_pk_mul_f32 v[222:223], v[222:223], v[130:131]
	global_store_dwordx4 v[42:43], v[216:219], off offset:2048 nt
	global_store_dwordx4 v[42:43], v[220:223], off offset:3072 nt
	s_nop 1
	v_lshl_add_u64 v[32:33], v[32:33], 0, s[6:7]
	s_mov_b32 s14, s15
	s_branch .Lfin_loop
.Lfin_last_a:
	s_waitcnt vmcnt(0)
	v_fmamk_f32 v36, v196, 0x39800000, v13
	v_rsq_f32_e32 v36, v36
	v_lshl_add_u64 v[38:39], v[32:33], 0, s[16:17]
	v_lshl_add_u64 v[40:41], v[32:33], 0, s[18:19]
	v_lshl_add_u64 v[42:43], v[32:33], 0, s[20:21]
	v_lshlrev_b32_e32 v216, 16, v132
	v_and_b32_e32 v217, 0xffff0000, v132
	v_lshlrev_b32_e32 v218, 16, v133
	v_and_b32_e32 v219, 0xffff0000, v133
	v_lshlrev_b32_e32 v220, 16, v134
	v_and_b32_e32 v221, 0xffff0000, v134
	v_lshlrev_b32_e32 v222, 16, v135
	v_and_b32_e32 v223, 0xffff0000, v135
	v_pk_mul_f32 v[216:217], v[36:37], v[216:217] op_sel_hi:[0,1]
	v_pk_mul_f32 v[218:219], v[36:37], v[218:219] op_sel_hi:[0,1]
	v_pk_mul_f32 v[220:221], v[36:37], v[220:221] op_sel_hi:[0,1]
	v_pk_mul_f32 v[222:223], v[36:37], v[222:223] op_sel_hi:[0,1]
	v_pk_mul_f32 v[216:217], v[216:217], v[68:69]
	v_pk_mul_f32 v[218:219], v[218:219], v[70:71]
	v_pk_mul_f32 v[220:221], v[220:221], v[72:73]
	v_pk_mul_f32 v[222:223], v[222:223], v[74:75]
	global_store_dwordx4 v[32:33], v[216:219], off nt
	global_store_dwordx4 v[32:33], v[220:223], off offset:1024 nt
	s_nop 1
	v_lshlrev_b32_e32 v216, 16, v136
	v_and_b32_e32 v217, 0xffff0000, v136
	v_lshlrev_b32_e32 v218, 16, v137
	v_and_b32_e32 v219, 0xffff0000, v137
	v_lshlrev_b32_e32 v220, 16, v138
	v_and_b32_e32 v221, 0xffff0000, v138
	v_lshlrev_b32_e32 v222, 16, v139
	v_and_b32_e32 v223, 0xffff0000, v139
	v_pk_mul_f32 v[216:217], v[36:37], v[216:217] op_sel_hi:[0,1]
	v_pk_mul_f32 v[218:219], v[36:37], v[218:219] op_sel_hi:[0,1]
	v_pk_mul_f32 v[220:221], v[36:37], v[220:221] op_sel_hi:[0,1]
	v_pk_mul_f32 v[222:223], v[36:37], v[222:223] op_sel_hi:[0,1]
	v_pk_mul_f32 v[216:217], v[216:217], v[76:77]
	v_pk_mul_f32 v[218:219], v[218:219], v[78:79]
	v_pk_mul_f32 v[220:221], v[220:221], v[80:81]
	v_pk_mul_f32 v[222:223], v[222:223], v[82:83]
	global_store_dwordx4 v[32:33], v[216:219], off offset:2048 nt
	global_store_dwordx4 v[32:33], v[220:223], off offset:3072 nt
	s_nop 1
	v_lshlrev_b32_e32 v216, 16, v140
	v_and_b32_e32 v217, 0xffff0000, v140
	v_lshlrev_b32_e32 v218, 16, v141
	v_and_b32_e32 v219, 0xffff0000, v141
	v_lshlrev_b32_e32 v220, 16, v142
	v_and_b32_e32 v221, 0xffff0000, v142
	v_lshlrev_b32_e32 v222, 16, v143
	v_and_b32_e32 v223, 0xffff0000, v143
	v_pk_mul_f32 v[216:217], v[36:37], v[216:217] op_sel_hi:[0,1]
	v_pk_mul_f32 v[218:219], v[36:37], v[218:219] op_sel_hi:[0,1]
	v_pk_mul_f32 v[220:221], v[36:37], v[220:221] op_sel_hi:[0,1]
	v_pk_mul_f32 v[222:223], v[36:37], v[222:223] op_sel_hi:[0,1]
	v_pk_mul_f32 v[216:217], v[216:217], v[84:85]
	v_pk_mul_f32 v[218:219], v[218:219], v[86:87]
	v_pk_mul_f32 v[220:221], v[220:221], v[88:89]
	v_pk_mul_f32 v[222:223], v[222:223], v[90:91]
	global_store_dwordx4 v[38:39], v[216:219], off nt
	global_store_dwordx4 v[38:39], v[220:223], off offset:1024 nt
	s_nop 1
	v_lshlrev_b32_e32 v216, 16, v144
	v_and_b32_e32 v217, 0xffff0000, v144
	v_lshlrev_b32_e32 v218, 16, v145
	v_and_b32_e32 v219, 0xffff0000, v145
	v_lshlrev_b32_e32 v220, 16, v146
	v_and_b32_e32 v221, 0xffff0000, v146
	v_lshlrev_b32_e32 v222, 16, v147
	v_and_b32_e32 v223, 0xffff0000, v147
	v_pk_mul_f32 v[216:217], v[36:37], v[216:217] op_sel_hi:[0,1]
	v_pk_mul_f32 v[218:219], v[36:37], v[218:219] op_sel_hi:[0,1]
	v_pk_mul_f32 v[220:221], v[36:37], v[220:221] op_sel_hi:[0,1]
	v_pk_mul_f32 v[222:223], v[36:37], v[222:223] op_sel_hi:[0,1]
	v_pk_mul_f32 v[216:217], v[216:217], v[92:93]
	v_pk_mul_f32 v[218:219], v[218:219], v[94:95]
	v_pk_mul_f32 v[220:221], v[220:221], v[96:97]
	v_pk_mul_f32 v[222:223], v[222:223], v[98:99]
	global_store_dwordx4 v[38:39], v[216:219], off offset:2048 nt
	global_store_dwordx4 v[38:39], v[220:223], off offset:3072 nt
	s_nop 1
	v_lshlrev_b32_e32 v216, 16, v148
	v_and_b32_e32 v217, 0xffff0000, v148
	v_lshlrev_b32_e32 v218, 16, v149
	v_and_b32_e32 v219, 0xffff0000, v149
	v_lshlrev_b32_e32 v220, 16, v150
	v_and_b32_e32 v221, 0xffff0000, v150
	v_lshlrev_b32_e32 v222, 16, v151
	v_and_b32_e32 v223, 0xffff0000, v151
	v_pk_mul_f32 v[216:217], v[36:37], v[216:217] op_sel_hi:[0,1]
	v_pk_mul_f32 v[218:219], v[36:37], v[218:219] op_sel_hi:[0,1]
; __device__ __forceinline__ void final_pass(const Params& p, int G) {
;     ...
;         for (int j = 0; j < 8; ++j) { const u32x4 w = hv[j]; const f32x4 g0 = gr[128 * j], g1 = gr[128 * j + 1];
;             const f32x4 v0 = (f32x4){__builtin_bit_cast(float, w.x << 16), __builtin_bit_cast(float, w.x & 0xffff0000u), __builtin_bit_cast(float, w.y << 16), __builtin_bit_cast(float, w.y & 0xffff0000u)};
;             const f32x4 v1 = (f32x4){__builtin_bit_cast(float, w.z << 16), __builtin_bit_cast(float, w.z & 0xffff0000u), __builtin_bit_cast(float, w.w << 16), __builtin_bit_cast(float, w.w & 0xffff0000u)};
;             __builtin_nontemporal_store(v0 * rstd * g0, xr + 128 * j); __builtin_nontemporal_store(v1 * rstd * g1, xr + 128 * j + 1); }
	v_pk_mul_f32 v[220:221], v[36:37], v[220:221] op_sel_hi:[0,1]
	v_pk_mul_f32 v[222:223], v[36:37], v[222:223] op_sel_hi:[0,1]
	v_pk_mul_f32 v[216:217], v[216:217], v[100:101]
	v_pk_mul_f32 v[218:219], v[218:219], v[102:103]
	v_pk_mul_f32 v[220:221], v[220:221], v[104:105]
	v_pk_mul_f32 v[222:223], v[222:223], v[106:107]
	global_store_dwordx4 v[40:41], v[216:219], off nt
	global_store_dwordx4 v[40:41], v[220:223], off offset:1024 nt
	s_nop 1
	v_lshlrev_b32_e32 v216, 16, v152
	v_and_b32_e32 v217, 0xffff0000, v152
	v_lshlrev_b32_e32 v218, 16, v153
	v_and_b32_e32 v219, 0xffff0000, v153
	v_lshlrev_b32_e32 v220, 16, v154
	v_and_b32_e32 v221, 0xffff0000, v154
	v_lshlrev_b32_e32 v222, 16, v155
	v_and_b32_e32 v223, 0xffff0000, v155
	v_pk_mul_f32 v[216:217], v[36:37], v[216:217] op_sel_hi:[0,1]
	v_pk_mul_f32 v[218:219], v[36:37], v[218:219] op_sel_hi:[0,1]
	v_pk_mul_f32 v[220:221], v[36:37], v[220:221] op_sel_hi:[0,1]
	v_pk_mul_f32 v[222:223], v[36:37], v[222:223] op_sel_hi:[0,1]
	v_pk_mul_f32 v[216:217], v[216:217], v[108:109]
	v_pk_mul_f32 v[218:219], v[218:219], v[110:111]
	v_pk_mul_f32 v[220:221], v[220:221], v[112:113]
	v_pk_mul_f32 v[222:223], v[222:223], v[114:115]
	global_store_dwordx4 v[40:41], v[216:219], off offset:2048 nt
	global_store_dwordx4 v[40:41], v[220:223], off offset:3072 nt
	s_nop 1
	v_lshlrev_b32_e32 v216, 16, v156
	v_and_b32_e32 v217, 0xffff0000, v156
	v_lshlrev_b32_e32 v218, 16, v157
	v_and_b32_e32 v219, 0xffff0000, v157
	v_lshlrev_b32_e32 v220, 16, v158
	v_and_b32_e32 v221, 0xffff0000, v158
	v_lshlrev_b32_e32 v222, 16, v159
	v_and_b32_e32 v223, 0xffff0000, v159
	v_pk_mul_f32 v[216:217], v[36:37], v[216:217] op_sel_hi:[0,1]
	v_pk_mul_f32 v[218:219], v[36:37], v[218:219] op_sel_hi:[0,1]
	v_pk_mul_f32 v[220:221], v[36:37], v[220:221] op_sel_hi:[0,1]
	v_pk_mul_f32 v[222:223], v[36:37], v[222:223] op_sel_hi:[0,1]
	v_pk_mul_f32 v[216:217], v[216:217], v[116:117]
	v_pk_mul_f32 v[218:219], v[218:219], v[118:119]
	v_pk_mul_f32 v[220:221], v[220:221], v[120:121]
	v_pk_mul_f32 v[222:223], v[222:223], v[122:123]
	global_store_dwordx4 v[42:43], v[216:219], off nt
	global_store_dwordx4 v[42:43], v[220:223], off offset:1024 nt
	s_nop 1
	v_lshlrev_b32_e32 v216, 16, v160
	v_and_b32_e32 v217, 0xffff0000, v160
	v_lshlrev_b32_e32 v218, 16, v161
	v_and_b32_e32 v219, 0xffff0000, v161
	v_lshlrev_b32_e32 v220, 16, v162
	v_and_b32_e32 v221, 0xffff0000, v162
	v_lshlrev_b32_e32 v222, 16, v163
	v_and_b32_e32 v223, 0xffff0000, v163
	v_pk_mul_f32 v[216:217], v[36:37], v[216:217] op_sel_hi:[0,1]
	v_pk_mul_f32 v[218:219], v[36:37], v[218:219] op_sel_hi:[0,1]
	v_pk_mul_f32 v[220:221], v[36:37], v[220:221] op_sel_hi:[0,1]
	v_pk_mul_f32 v[222:223], v[36:37], v[222:223] op_sel_hi:[0,1]
	v_pk_mul_f32 v[216:217], v[216:217], v[124:125]
	v_pk_mul_f32 v[218:219], v[218:219], v[126:127]
	v_pk_mul_f32 v[220:221], v[220:221], v[128:129]
	v_pk_mul_f32 v[222:223], v[222:223], v[130:131]
	global_store_dwordx4 v[42:43], v[216:219], off offset:2048 nt
	global_store_dwordx4 v[42:43], v[220:223], off offset:3072 nt
	s_nop 1
	v_lshl_add_u64 v[32:33], v[32:33], 0, s[6:7]
	s_branch .LBB0_1055
.Lfin_last_b:
	s_waitcnt vmcnt(0)
	v_fmamk_f32 v36, v197, 0x39800000, v13
	v_rsq_f32_e32 v36, v36
	v_lshl_add_u64 v[38:39], v[32:33], 0, s[16:17]
	v_lshl_add_u64 v[40:41], v[32:33], 0, s[18:19]
	v_lshl_add_u64 v[42:43], v[32:33], 0, s[20:21]
	v_lshlrev_b32_e32 v216, 16, v164
	v_and_b32_e32 v217, 0xffff0000, v164
	v_lshlrev_b32_e32 v218, 16, v165
	v_and_b32_e32 v219, 0xffff0000, v165
	v_lshlrev_b32_e32 v220, 16, v166
	v_and_b32_e32 v221, 0xffff0000, v166
	v_lshlrev_b32_e32 v222, 16, v167
	v_and_b32_e32 v223, 0xffff0000, v167
	v_pk_mul_f32 v[216:217], v[36:37], v[216:217] op_sel_hi:[0,1]
	v_pk_mul_f32 v[218:219], v[36:37], v[218:219] op_sel_hi:[0,1]
	v_pk_mul_f32 v[220:221], v[36:37], v[220:221] op_sel_hi:[0,1]
	v_pk_mul_f32 v[222:223], v[36:37], v[222:223] op_sel_hi:[0,1]
	v_pk_mul_f32 v[216:217], v[216:217], v[68:69]
	v_pk_mul_f32 v[218:219], v[218:219], v[70:71]
	v_pk_mul_f32 v[220:221], v[220:221], v[72:73]
	v_pk_mul_f32 v[222:223], v[222:223], v[74:75]
	global_store_dwordx4 v[32:33], v[216:219], off nt
	global_store_dwordx4 v[32:33], v[220:223], off offset:1024 nt
	s_nop 1
	v_lshlrev_b32_e32 v216, 16, v168
	v_and_b32_e32 v217, 0xffff0000, v168
	v_lshlrev_b32_e32 v218, 16, v169
	v_and_b32_e32 v219, 0xffff0000, v169
	v_lshlrev_b32_e32 v220, 16, v170
	v_and_b32_e32 v221, 0xffff0000, v170
	v_lshlrev_b32_e32 v222, 16, v171
	v_and_b32_e32 v223, 0xffff0000, v171
	v_pk_mul_f32 v[216:217], v[36:37], v[216:217] op_sel_hi:[0,1]
	v_pk_mul_f32 v[218:219], v[36:37], v[218:219] op_sel_hi:[0,1]
	v_pk_mul_f32 v[220:221], v[36:37], v[220:221] op_sel_hi:[0,1]
	v_pk_mul_f32 v[222:223], v[36:37], v[222:223] op_sel_hi:[0,1]
	v_pk_mul_f32 v[216:217], v[216:217], v[76:77]
	v_pk_mul_f32 v[218:219], v[218:219], v[78:79]
	v_pk_mul_f32 v[220:221], v[220:221], v[80:81]
	v_pk_mul_f32 v[222:223], v[222:223], v[82:83]
	global_store_dwordx4 v[32:33], v[216:219], off offset:2048 nt
	global_store_dwordx4 v[32:33], v[220:223], off offset:3072 nt
	s_nop 1
	v_lshlrev_b32_e32 v216, 16, v172
	v_and_b32_e32 v217, 0xffff0000, v172
; __device__ __forceinline__ void final_pass(const Params& p, int G) {
;     ...
;         for (int j = 0; j < 8; ++j) { const u32x4 w = hv[j]; const f32x4 g0 = gr[128 * j], g1 = gr[128 * j + 1];
;             const f32x4 v0 = (f32x4){__builtin_bit_cast(float, w.x << 16), __builtin_bit_cast(float, w.x & 0xffff0000u), __builtin_bit_cast(float, w.y << 16), __builtin_bit_cast(float, w.y & 0xffff0000u)};
;             const f32x4 v1 = (f32x4){__builtin_bit_cast(float, w.z << 16), __builtin_bit_cast(float, w.z & 0xffff0000u), __builtin_bit_cast(float, w.w << 16), __builtin_bit_cast(float, w.w & 0xffff0000u)};
;             __builtin_nontemporal_store(v0 * rstd * g0, xr + 128 * j); __builtin_nontemporal_store(v1 * rstd * g1, xr + 128 * j + 1); }
	v_lshlrev_b32_e32 v218, 16, v173
	v_and_b32_e32 v219, 0xffff0000, v173
	v_lshlrev_b32_e32 v220, 16, v174
	v_and_b32_e32 v221, 0xffff0000, v174
	v_lshlrev_b32_e32 v222, 16, v175
	v_and_b32_e32 v223, 0xffff0000, v175
	v_pk_mul_f32 v[216:217], v[36:37], v[216:217] op_sel_hi:[0,1]
	v_pk_mul_f32 v[218:219], v[36:37], v[218:219] op_sel_hi:[0,1]
	v_pk_mul_f32 v[220:221], v[36:37], v[220:221] op_sel_hi:[0,1]
	v_pk_mul_f32 v[222:223], v[36:37], v[222:223] op_sel_hi:[0,1]
	v_pk_mul_f32 v[216:217], v[216:217], v[84:85]
	v_pk_mul_f32 v[218:219], v[218:219], v[86:87]
	v_pk_mul_f32 v[220:221], v[220:221], v[88:89]
	v_pk_mul_f32 v[222:223], v[222:223], v[90:91]
	global_store_dwordx4 v[38:39], v[216:219], off nt
	global_store_dwordx4 v[38:39], v[220:223], off offset:1024 nt
	s_nop 1
	v_lshlrev_b32_e32 v216, 16, v176
	v_and_b32_e32 v217, 0xffff0000, v176
	v_lshlrev_b32_e32 v218, 16, v177
	v_and_b32_e32 v219, 0xffff0000, v177
	v_lshlrev_b32_e32 v220, 16, v178
	v_and_b32_e32 v221, 0xffff0000, v178
	v_lshlrev_b32_e32 v222, 16, v179
	v_and_b32_e32 v223, 0xffff0000, v179
	v_pk_mul_f32 v[216:217], v[36:37], v[216:217] op_sel_hi:[0,1]
	v_pk_mul_f32 v[218:219], v[36:37], v[218:219] op_sel_hi:[0,1]
	v_pk_mul_f32 v[220:221], v[36:37], v[220:221] op_sel_hi:[0,1]
	v_pk_mul_f32 v[222:223], v[36:37], v[222:223] op_sel_hi:[0,1]
	v_pk_mul_f32 v[216:217], v[216:217], v[92:93]
	v_pk_mul_f32 v[218:219], v[218:219], v[94:95]
	v_pk_mul_f32 v[220:221], v[220:221], v[96:97]
	v_pk_mul_f32 v[222:223], v[222:223], v[98:99]
	global_store_dwordx4 v[38:39], v[216:219], off offset:2048 nt
	global_store_dwordx4 v[38:39], v[220:223], off offset:3072 nt
	s_nop 1
	v_lshlrev_b32_e32 v216, 16, v180
	v_and_b32_e32 v217, 0xffff0000, v180
	v_lshlrev_b32_e32 v218, 16, v181
	v_and_b32_e32 v219, 0xffff0000, v181
	v_lshlrev_b32_e32 v220, 16, v182
	v_and_b32_e32 v221, 0xffff0000, v182
	v_lshlrev_b32_e32 v222, 16, v183
	v_and_b32_e32 v223, 0xffff0000, v183
	v_pk_mul_f32 v[216:217], v[36:37], v[216:217] op_sel_hi:[0,1]
	v_pk_mul_f32 v[218:219], v[36:37], v[218:219] op_sel_hi:[0,1]
	v_pk_mul_f32 v[220:221], v[36:37], v[220:221] op_sel_hi:[0,1]
	v_pk_mul_f32 v[222:223], v[36:37], v[222:223] op_sel_hi:[0,1]
	v_pk_mul_f32 v[216:217], v[216:217], v[100:101]
	v_pk_mul_f32 v[218:219], v[218:219], v[102:103]
	v_pk_mul_f32 v[220:221], v[220:221], v[104:105]
	v_pk_mul_f32 v[222:223], v[222:223], v[106:107]
	global_store_dwordx4 v[40:41], v[216:219], off nt
	global_store_dwordx4 v[40:41], v[220:223], off offset:1024 nt
	s_nop 1
	v_lshlrev_b32_e32 v216, 16, v184
	v_and_b32_e32 v217, 0xffff0000, v184
	v_lshlrev_b32_e32 v218, 16, v185
	v_and_b32_e32 v219, 0xffff0000, v185
	v_lshlrev_b32_e32 v220, 16, v186
	v_and_b32_e32 v221, 0xffff0000, v186
	v_lshlrev_b32_e32 v222, 16, v187
	v_and_b32_e32 v223, 0xffff0000, v187
	v_pk_mul_f32 v[216:217], v[36:37], v[216:217] op_sel_hi:[0,1]
	v_pk_mul_f32 v[218:219], v[36:37], v[218:219] op_sel_hi:[0,1]
	v_pk_mul_f32 v[220:221], v[36:37], v[220:221] op_sel_hi:[0,1]
	v_pk_mul_f32 v[222:223], v[36:37], v[222:223] op_sel_hi:[0,1]
	v_pk_mul_f32 v[216:217], v[216:217], v[108:109]
	v_pk_mul_f32 v[218:219], v[218:219], v[110:111]
	v_pk_mul_f32 v[220:221], v[220:221], v[112:113]
	v_pk_mul_f32 v[222:223], v[222:223], v[114:115]
	global_store_dwordx4 v[40:41], v[216:219], off offset:2048 nt
	global_store_dwordx4 v[40:41], v[220:223], off offset:3072 nt
	s_nop 1
	v_lshlrev_b32_e32 v216, 16, v188
	v_and_b32_e32 v217, 0xffff0000, v188
	v_lshlrev_b32_e32 v218, 16, v189
	v_and_b32_e32 v219, 0xffff0000, v189
	v_lshlrev_b32_e32 v220, 16, v190
	v_and_b32_e32 v221, 0xffff0000, v190
	v_lshlrev_b32_e32 v222, 16, v191
	v_and_b32_e32 v223, 0xffff0000, v191
	v_pk_mul_f32 v[216:217], v[36:37], v[216:217] op_sel_hi:[0,1]
	v_pk_mul_f32 v[218:219], v[36:37], v[218:219] op_sel_hi:[0,1]
	v_pk_mul_f32 v[220:221], v[36:37], v[220:221] op_sel_hi:[0,1]
	v_pk_mul_f32 v[222:223], v[36:37], v[222:223] op_sel_hi:[0,1]
	v_pk_mul_f32 v[216:217], v[216:217], v[116:117]
	v_pk_mul_f32 v[218:219], v[218:219], v[118:119]
	v_pk_mul_f32 v[220:221], v[220:221], v[120:121]
	v_pk_mul_f32 v[222:223], v[222:223], v[122:123]
	global_store_dwordx4 v[42:43], v[216:219], off nt
	global_store_dwordx4 v[42:43], v[220:223], off offset:1024 nt
	s_nop 1
	v_lshlrev_b32_e32 v216, 16, v192
	v_and_b32_e32 v217, 0xffff0000, v192
	v_lshlrev_b32_e32 v218, 16, v193
	v_and_b32_e32 v219, 0xffff0000, v193
	v_lshlrev_b32_e32 v220, 16, v194
	v_and_b32_e32 v221, 0xffff0000, v194
	v_lshlrev_b32_e32 v222, 16, v195
	v_and_b32_e32 v223, 0xffff0000, v195
	v_pk_mul_f32 v[216:217], v[36:37], v[216:217] op_sel_hi:[0,1]
	v_pk_mul_f32 v[218:219], v[36:37], v[218:219] op_sel_hi:[0,1]
	v_pk_mul_f32 v[220:221], v[36:37], v[220:221] op_sel_hi:[0,1]
	v_pk_mul_f32 v[222:223], v[36:37], v[222:223] op_sel_hi:[0,1]
	v_pk_mul_f32 v[216:217], v[216:217], v[124:125]
	v_pk_mul_f32 v[218:219], v[218:219], v[126:127]
	v_pk_mul_f32 v[220:221], v[220:221], v[128:129]
	v_pk_mul_f32 v[222:223], v[222:223], v[130:131]
	global_store_dwordx4 v[42:43], v[216:219], off offset:2048 nt
	global_store_dwordx4 v[42:43], v[220:223], off offset:3072 nt
	s_nop 1
	v_lshl_add_u64 v[32:33], v[32:33], 0, s[6:7]
